# G3 part-unit epilogue: 8 row-scale loads hoisted (was a vmcnt(0) drain per row); grid barriers 2..10 rewritten: fixed XCD leader, non-returning arrival adds, poll the top counter directly
# speedup vs baseline: 1.0092x; 1.0038x over previous
.LBB0_2:
	s_or_b64 exec, exec, s[4:5]
	s_add_u32 s4, s30, 0x8ce000
	s_addc_u32 s5, s31, 0
	s_waitcnt lgkmcnt(0)
	s_barrier
	v_writelane_b32 v254, s4, 3
	s_getreg_b32 s3, hwreg(HW_REG_XCC_ID, 0, 4)
	s_nop 0
	v_writelane_b32 v254, s5, 4
	s_mov_b64 s[4:5], exec
	v_readlane_b32 s8, v254, 1
	v_readlane_b32 s9, v254, 2
	s_and_b64 s[8:9], s[4:5], s[8:9]
	s_mov_b64 exec, s[8:9]
	s_cbranch_execz .LBB0_5
	s_mov_b64 s[8:9], exec
	v_mbcnt_lo_u32_b32 v1, s8, 0
	v_mbcnt_hi_u32_b32 v1, s9, v1
	v_cmp_eq_u32_e32 vcc, 0, v1
	s_and_b64 s[10:11], exec, vcc
	s_mov_b64 exec, s[10:11]
	s_cbranch_execz .LBB0_5
	s_lshl_b32 s3, s3, 8
	s_bcnt1_i32_b64 s8, s[8:9]
	s_and_b32 s3, s3, 0xf00
	v_mov_b32_e32 v2, s8
	v_readlane_b32 s8, v254, 3
	v_mov_b32_e32 v1, s3
	v_readlane_b32 s9, v254, 4
	s_nop 4
	global_atomic_add v1, v1, v2, s[8:9] offset:1024 sc0
	s_waitcnt vmcnt(0)
	v_cmp_eq_u32_e32 vcc, 0, v1
	s_add_i32 s3, 0, 0x25008
	s_nop 0
	v_cndmask_b32_e64 v1, 0, 1, vcc
	v_mov_b32_e32 v2, s3
	ds_write_b32 v2, v1
	s_waitcnt lgkmcnt(0)

.LBB0_216:
	s_getreg_b32 s3, hwreg(HW_REG_XCC_ID, 0, 4)
	s_waitcnt vmcnt(0)
	s_barrier
	s_mov_b64 s[0:1], exec
	v_readlane_b32 s4, v254, 1
	v_readlane_b32 s5, v254, 2
	s_and_b64 s[4:5], s[0:1], s[4:5]
	s_mov_b64 exec, s[4:5]
	s_cbranch_execz .LBB0_268
	s_and_b32 s18, s3, 15
	s_lshl_b32 s18, s18, 8
	s_add_u32 s12, s30, 0x8d1400
	s_addc_u32 s13, s31, 0
	s_add_u32 s10, s30, 0x8cf400
	s_addc_u32 s11, s31, 0
	s_add_u32 s10, s10, s18
	s_addc_u32 s11, s11, 0
	v_mov_b32_e32 v0, 0x25000
	ds_read_b32 v2, v0
	ds_read_b32 v3, v0 offset:4
	ds_read_b32 v4, v0 offset:8
	v_mov_b32_e32 v1, 1
	v_mov_b32_e32 v5, 0
	global_atomic_add v5, v1, s[10:11]
	s_waitcnt lgkmcnt(0)
	v_readfirstlane_b32 s14, v2
	v_readfirstlane_b32 s15, v3
	v_readfirstlane_b32 s16, v4
	s_nop 3
	s_mul_i32 s14, s14, 2
	s_mul_i32 s15, s15, 2
	s_mov_b32 s17, 0
	s_cmp_eq_u32 s16, 0
	s_cbranch_scc1 .Lxb2_w
.Lxb2_a:
	global_load_dword v6, v5, s[10:11] sc1
	s_waitcnt vmcnt(0)
	v_readfirstlane_b32 s19, v6
	s_nop 3
	s_cmp_ge_u32 s19, s14
	s_cbranch_scc1 .Lxb2_ad
	s_sleep 1
	s_add_u32 s17, s17, 1
	s_cmp_lt_u32 s17, 0x20000
	s_cbranch_scc1 .Lxb2_a
.Lxb2_ad:
	buffer_wbl2 sc1
	s_waitcnt vmcnt(0)
	global_atomic_add v5, v1, s[12:13]
.Lxb2_w:
	global_load_dword v6, v5, s[12:13] sc1
	s_waitcnt vmcnt(0)
	v_readfirstlane_b32 s19, v6
	s_nop 3
	s_cmp_ge_u32 s19, s15
	s_cbranch_scc1 .Lxb2_wd
	s_sleep 1
	s_add_u32 s17, s17, 1
	s_cmp_lt_u32 s17, 0x40000
	s_cbranch_scc1 .Lxb2_w
.Lxb2_wd:
	buffer_inv sc1
	s_waitcnt vmcnt(0)

.LBB0_545:
	s_getreg_b32 s3, hwreg(HW_REG_XCC_ID, 0, 4)
	s_waitcnt vmcnt(0)
	s_waitcnt vmcnt(0) lgkmcnt(0)
	s_barrier
	s_mov_b64 s[0:1], exec
	v_readlane_b32 s4, v254, 1
	v_readlane_b32 s5, v254, 2
	s_and_b64 s[4:5], s[0:1], s[4:5]
	s_mov_b64 exec, s[4:5]
	s_cbranch_execz .LBB0_597
	s_and_b32 s18, s3, 15
	s_lshl_b32 s18, s18, 8
	s_add_u32 s12, s30, 0x8d1400
	s_addc_u32 s13, s31, 0
	s_add_u32 s10, s30, 0x8cf400
	s_addc_u32 s11, s31, 0
	s_add_u32 s10, s10, s18
	s_addc_u32 s11, s11, 0
	v_mov_b32_e32 v0, 0x25000
	ds_read_b32 v2, v0
	ds_read_b32 v3, v0 offset:4
	ds_read_b32 v4, v0 offset:8
	v_mov_b32_e32 v1, 1
	v_mov_b32_e32 v5, 0
	global_atomic_add v5, v1, s[10:11]
	s_waitcnt lgkmcnt(0)
	v_readfirstlane_b32 s14, v2
	v_readfirstlane_b32 s15, v3
	v_readfirstlane_b32 s16, v4
	s_nop 3
	s_mul_i32 s14, s14, 3
	s_mul_i32 s15, s15, 3
	s_mov_b32 s17, 0
	s_cmp_eq_u32 s16, 0
	s_cbranch_scc1 .Lxb3_w

.LBB0_687:
	s_getreg_b32 s3, hwreg(HW_REG_XCC_ID, 0, 4)
	s_waitcnt vmcnt(0)
	s_barrier
	s_mov_b64 s[0:1], exec
	v_readlane_b32 s4, v254, 1
	v_readlane_b32 s5, v254, 2
	s_and_b64 s[4:5], s[0:1], s[4:5]
	s_mov_b64 exec, s[4:5]
	s_cbranch_execz .LBB0_739
	s_and_b32 s18, s3, 15
	s_lshl_b32 s18, s18, 8
	s_add_u32 s12, s30, 0x8d1400
	s_addc_u32 s13, s31, 0
	s_add_u32 s10, s30, 0x8cf400
	s_addc_u32 s11, s31, 0
	s_add_u32 s10, s10, s18
	s_addc_u32 s11, s11, 0
	v_mov_b32_e32 v0, 0x25000
	ds_read_b32 v2, v0
	ds_read_b32 v3, v0 offset:4
	ds_read_b32 v4, v0 offset:8
	v_mov_b32_e32 v1, 1
	v_mov_b32_e32 v5, 0
	global_atomic_add v5, v1, s[10:11]
	s_waitcnt lgkmcnt(0)
	v_readfirstlane_b32 s14, v2
	v_readfirstlane_b32 s15, v3
	v_readfirstlane_b32 s16, v4
	s_nop 3
	s_mul_i32 s14, s14, 4
	s_mul_i32 s15, s15, 4
	s_mov_b32 s17, 0
	s_cmp_eq_u32 s16, 0
	s_cbranch_scc1 .Lxb4_w

.LBB0_753:
	s_or_b64 exec, exec, s[4:5]
	s_getreg_b32 s3, hwreg(HW_REG_XCC_ID, 0, 4)
	s_waitcnt vmcnt(0)
	s_barrier
	s_mov_b64 s[0:1], exec
	v_readlane_b32 s4, v254, 1
	v_readlane_b32 s5, v254, 2
	s_and_b64 s[4:5], s[0:1], s[4:5]
	s_mov_b64 exec, s[4:5]
	s_cbranch_execz .LBB0_805
	s_and_b32 s18, s3, 15
	s_lshl_b32 s18, s18, 8
	s_add_u32 s12, s30, 0x8d1400
	s_addc_u32 s13, s31, 0
	s_add_u32 s10, s30, 0x8cf400
	s_addc_u32 s11, s31, 0
	s_add_u32 s10, s10, s18
	s_addc_u32 s11, s11, 0
	v_mov_b32_e32 v0, 0x25000
	ds_read_b32 v2, v0
	ds_read_b32 v3, v0 offset:4
	ds_read_b32 v4, v0 offset:8
	v_mov_b32_e32 v1, 1
	v_mov_b32_e32 v5, 0
	global_atomic_add v5, v1, s[10:11]
	s_waitcnt lgkmcnt(0)
	v_readfirstlane_b32 s14, v2
	v_readfirstlane_b32 s15, v3
	v_readfirstlane_b32 s16, v4
	s_nop 3
	s_mul_i32 s14, s14, 5
	s_mul_i32 s15, s15, 5
	s_mov_b32 s17, 0
	s_cmp_eq_u32 s16, 0
	s_cbranch_scc1 .Lxb5_w

.LBB0_895:
	s_getreg_b32 s3, hwreg(HW_REG_XCC_ID, 0, 4)
	s_waitcnt vmcnt(0)
	s_barrier
	s_mov_b64 s[0:1], exec
	v_readlane_b32 s4, v254, 1
	v_readlane_b32 s5, v254, 2
	s_and_b64 s[4:5], s[0:1], s[4:5]
	s_mov_b64 exec, s[4:5]
	s_cbranch_execz .LBB0_947
	s_and_b32 s18, s3, 15
	s_lshl_b32 s18, s18, 8
	s_add_u32 s12, s30, 0x8d1400
	s_addc_u32 s13, s31, 0
	s_add_u32 s10, s30, 0x8cf400
	s_addc_u32 s11, s31, 0
	s_add_u32 s10, s10, s18
	s_addc_u32 s11, s11, 0
	v_mov_b32_e32 v0, 0x25000
	ds_read_b32 v2, v0
	ds_read_b32 v3, v0 offset:4
	ds_read_b32 v4, v0 offset:8
	v_mov_b32_e32 v1, 1
	v_mov_b32_e32 v5, 0
	global_atomic_add v5, v1, s[10:11]
	s_waitcnt lgkmcnt(0)
	v_readfirstlane_b32 s14, v2
	v_readfirstlane_b32 s15, v3
	v_readfirstlane_b32 s16, v4
	s_nop 3
	s_mul_i32 s14, s14, 6
	s_mul_i32 s15, s15, 6
	s_mov_b32 s17, 0
	s_cmp_eq_u32 s16, 0
	s_cbranch_scc1 .Lxb6_w

.LBB0_972:
	s_addk_i32 s77, 0xf000
	s_lshr_b32 s1, s77, 12
	s_add_i32 s1, s1, 1
	s_cmp_gt_i32 s0, 15
	s_cselect_b32 s0, s1, 0
	s_mul_hi_u32 s1, s0, 0x6000
	s_mulk_i32 s0, 0x6000
	v_lshl_or_b32 v2, s38, 8, v192
	s_add_u32 s0, s64, s0
	s_addc_u32 s1, s65, s1
	v_ashrrev_i32_e32 v3, 31, v2
	v_lshl_add_u64 v[136:137], v[2:3], 2, s[0:1]
	global_load_dwordx4 v[140:143], v[136:137], off offset:16
	global_load_dwordx4 v[144:147], v[136:137], off
	global_load_dwordx4 v[132:135], v[136:137], off offset:528
	s_nop 0
	global_load_dwordx4 v[136:139], v[136:137], off offset:512
	s_cmp_lg_u32 s74, 32
	s_cselect_b64 s[0:1], -1, 0
	s_cmp_lt_i32 s73, 2
	s_cselect_b64 s[40:41], -1, 0
	s_and_b64 s[40:41], s[0:1], s[40:41]
	v_cndmask_b32_e64 v1, 0, 1, s[40:41]
	v_mov_b32_e32 v188, 1.0
	v_cmp_ne_u32_e64 s[0:1], 1, v1
	s_andn2_b64 vcc, exec, s[40:41]
	v_mov_b32_e32 v190, 1.0
	s_cbranch_vccnz .LBB0_974
	global_load_dwordx4 v[202:205], v[186:187], off
	global_load_dwordx4 v[206:209], v[182:183], off
	global_load_dwordx4 v[210:213], v[178:179], off
	global_load_dwordx4 v[214:217], v[174:175], off
	global_load_dwordx4 v[218:221], v[170:171], off
	global_load_dwordx4 v[222:225], v[166:167], off
	global_load_dwordx4 v[226:229], v[162:163], off
	global_load_dwordx4 v[230:233], v[158:159], off
	s_waitcnt vmcnt(0)
	v_add_f32_e32 v202, v202, v203
	v_add_f32_e32 v204, v204, v205
	v_add_f32_e32 v206, v206, v207
	v_add_f32_e32 v208, v208, v209
	v_add_f32_e32 v210, v210, v211
	v_add_f32_e32 v212, v212, v213
	v_add_f32_e32 v214, v214, v215
	v_add_f32_e32 v216, v216, v217
	v_add_f32_e32 v218, v218, v219
	v_add_f32_e32 v220, v220, v221
	v_add_f32_e32 v222, v222, v223
	v_add_f32_e32 v224, v224, v225
	v_add_f32_e32 v226, v226, v227
	v_add_f32_e32 v228, v228, v229
	v_add_f32_e32 v230, v230, v231
	v_add_f32_e32 v232, v232, v233
	v_add_f32_e32 v202, v202, v204
	v_add_f32_e32 v206, v206, v208
	v_add_f32_e32 v210, v210, v212
	v_add_f32_e32 v214, v214, v216
	v_add_f32_e32 v218, v218, v220
	v_add_f32_e32 v222, v222, v224
	v_add_f32_e32 v226, v226, v228
	v_add_f32_e32 v230, v230, v232
	v_fmamk_f32 v202, v202, 0x3a800000, v193
	v_fmamk_f32 v206, v206, 0x3a800000, v193
	v_fmamk_f32 v210, v210, 0x3a800000, v193
	v_fmamk_f32 v214, v214, 0x3a800000, v193
	v_fmamk_f32 v218, v218, 0x3a800000, v193
	v_fmamk_f32 v222, v222, 0x3a800000, v193
	v_fmamk_f32 v226, v226, 0x3a800000, v193
	v_fmamk_f32 v230, v230, 0x3a800000, v193
	v_rsq_f32_e32 v234, v202
	v_rsq_f32_e32 v235, v206
	v_rsq_f32_e32 v236, v210
	v_rsq_f32_e32 v237, v214
	v_rsq_f32_e32 v238, v218
	v_rsq_f32_e32 v239, v222
	v_rsq_f32_e32 v240, v226
	v_rsq_f32_e32 v241, v230
	s_nop 0
	v_mov_b32_e32 v190, v234
.LBB0_974:
	v_sub_co_u32_e64 v1, s[40:41], s73, 1
	s_nop 0
	v_readfirstlane_b32 s10, v1
	s_lshl_b64 s[42:43], s[10:11], 23
	s_add_u32 s10, s8, s42
	s_addc_u32 s17, s9, s43
	s_add_u32 s10, s10, 0xfe000000
	s_addc_u32 s17, s17, -1
	s_and_b64 s[40:41], s[40:41], exec
	s_cselect_b32 s17, s35, s17
	s_cselect_b32 s10, s34, s10
	v_mov_b32_e32 v186, s10
	v_mov_b32_e32 v187, s17
	v_lshl_add_u64 v[2:3], v[2:3], 1, v[186:187]
	v_lshlrev_b64 v[184:185], 11, v[184:185]
	s_waitcnt vmcnt(0)
	v_pk_mul_f32 v[130:131], v[130:131], v[146:147]
	v_pk_mul_f32 v[128:129], v[128:129], v[144:145]
	v_pk_mul_f32 v[126:127], v[126:127], v[142:143]
	v_pk_mul_f32 v[124:125], v[124:125], v[140:141]
	v_lshl_add_u64 v[184:185], v[2:3], 0, v[184:185]
	v_pk_mul_f32 v[130:131], v[130:131], v[190:191] op_sel_hi:[1,0]
	v_pk_mul_f32 v[128:129], v[128:129], v[190:191] op_sel_hi:[1,0]
	v_pk_mul_f32 v[186:187], v[126:127], v[190:191] op_sel_hi:[1,0]
	v_pk_mul_f32 v[126:127], v[124:125], v[190:191] op_sel_hi:[1,0]
	v_cvt_pk_bf16_f32 v124, v128, v129
	v_cvt_pk_bf16_f32 v125, v130, v131
	v_pk_mul_f32 v[118:119], v[118:119], v[134:135]
	v_pk_mul_f32 v[116:117], v[116:117], v[132:133]
	v_cvt_pk_bf16_f32 v126, v126, v127
	v_cvt_pk_bf16_f32 v127, v186, v187
	global_store_dwordx4 v[184:185], v[124:127], off
	v_pk_mul_f32 v[122:123], v[122:123], v[138:139]
	v_pk_mul_f32 v[120:121], v[120:121], v[136:137]
	v_pk_mul_f32 v[124:125], v[118:119], v[190:191] op_sel_hi:[1,0]
	v_pk_mul_f32 v[118:119], v[116:117], v[190:191] op_sel_hi:[1,0]
	s_and_b64 vcc, exec, s[0:1]
	s_mov_b64 s[78:79], s[84:85]
	v_pk_mul_f32 v[122:123], v[122:123], v[190:191] op_sel_hi:[1,0]
	v_pk_mul_f32 v[120:121], v[120:121], v[190:191] op_sel_hi:[1,0]
	s_nop 0
	v_cvt_pk_bf16_f32 v116, v120, v121
	v_cvt_pk_bf16_f32 v117, v122, v123
	v_cvt_pk_bf16_f32 v118, v118, v119
	v_cvt_pk_bf16_f32 v119, v124, v125
	global_store_dwordx4 v[184:185], v[116:119], off offset:256
	s_cbranch_vccnz .LBB0_976
	v_mov_b32_e32 v188, v235
.LBB0_976:
	s_nop 0
	v_lshlrev_b64 v[116:117], 11, v[180:181]
	v_pk_mul_f32 v[114:115], v[114:115], v[146:147]
	v_pk_mul_f32 v[112:113], v[112:113], v[144:145]
	v_pk_mul_f32 v[110:111], v[110:111], v[142:143]
	v_pk_mul_f32 v[108:109], v[108:109], v[140:141]
	v_lshl_add_u64 v[116:117], v[2:3], 0, v[116:117]
	v_pk_mul_f32 v[114:115], v[114:115], v[188:189] op_sel_hi:[1,0]
	v_pk_mul_f32 v[112:113], v[112:113], v[188:189] op_sel_hi:[1,0]
	v_pk_mul_f32 v[118:119], v[110:111], v[188:189] op_sel_hi:[1,0]
	v_pk_mul_f32 v[110:111], v[108:109], v[188:189] op_sel_hi:[1,0]
	v_cvt_pk_bf16_f32 v108, v112, v113
	v_cvt_pk_bf16_f32 v109, v114, v115
	v_pk_mul_f32 v[102:103], v[102:103], v[134:135]
	v_pk_mul_f32 v[100:101], v[100:101], v[132:133]
	v_cvt_pk_bf16_f32 v110, v110, v111
	v_cvt_pk_bf16_f32 v111, v118, v119
	global_store_dwordx4 v[116:117], v[108:111], off
	v_pk_mul_f32 v[106:107], v[106:107], v[138:139]
	v_pk_mul_f32 v[104:105], v[104:105], v[136:137]
	v_pk_mul_f32 v[108:109], v[102:103], v[188:189] op_sel_hi:[1,0]
	v_pk_mul_f32 v[102:103], v[100:101], v[188:189] op_sel_hi:[1,0]
	v_pk_mul_f32 v[106:107], v[106:107], v[188:189] op_sel_hi:[1,0]
	v_pk_mul_f32 v[104:105], v[104:105], v[188:189] op_sel_hi:[1,0]
	s_and_b64 vcc, exec, s[0:1]
	v_cvt_pk_bf16_f32 v100, v104, v105
	v_cvt_pk_bf16_f32 v101, v106, v107
	v_cvt_pk_bf16_f32 v102, v102, v103
	v_cvt_pk_bf16_f32 v103, v108, v109
	global_store_dwordx4 v[116:117], v[100:103], off offset:256
	s_nop 1
	v_mov_b32_e32 v100, 1.0
	v_mov_b32_e32 v102, 1.0
	s_cbranch_vccnz .LBB0_978
	v_mov_b32_e32 v102, v236
.LBB0_978:
	v_lshlrev_b64 v[104:105], 11, v[176:177]
	v_pk_mul_f32 v[98:99], v[98:99], v[146:147]
	v_pk_mul_f32 v[96:97], v[96:97], v[144:145]
	v_pk_mul_f32 v[94:95], v[94:95], v[142:143]
	v_pk_mul_f32 v[92:93], v[92:93], v[140:141]
	v_lshl_add_u64 v[104:105], v[2:3], 0, v[104:105]
	v_pk_mul_f32 v[98:99], v[98:99], v[102:103] op_sel_hi:[1,0]
	v_pk_mul_f32 v[96:97], v[96:97], v[102:103] op_sel_hi:[1,0]
	v_pk_mul_f32 v[106:107], v[94:95], v[102:103] op_sel_hi:[1,0]
	v_pk_mul_f32 v[94:95], v[92:93], v[102:103] op_sel_hi:[1,0]
	v_cvt_pk_bf16_f32 v92, v96, v97
	v_cvt_pk_bf16_f32 v93, v98, v99
	v_pk_mul_f32 v[86:87], v[86:87], v[134:135]
	v_pk_mul_f32 v[84:85], v[84:85], v[132:133]
	v_cvt_pk_bf16_f32 v94, v94, v95
	v_cvt_pk_bf16_f32 v95, v106, v107
	global_store_dwordx4 v[104:105], v[92:95], off
	v_pk_mul_f32 v[90:91], v[90:91], v[138:139]
	v_pk_mul_f32 v[88:89], v[88:89], v[136:137]
	v_pk_mul_f32 v[92:93], v[86:87], v[102:103] op_sel_hi:[1,0]
	v_pk_mul_f32 v[86:87], v[84:85], v[102:103] op_sel_hi:[1,0]
	s_and_b64 vcc, exec, s[0:1]
	v_pk_mul_f32 v[90:91], v[90:91], v[102:103] op_sel_hi:[1,0]
	v_pk_mul_f32 v[88:89], v[88:89], v[102:103] op_sel_hi:[1,0]
	s_nop 0
	v_cvt_pk_bf16_f32 v84, v88, v89
	v_cvt_pk_bf16_f32 v85, v90, v91
	v_cvt_pk_bf16_f32 v86, v86, v87
	v_cvt_pk_bf16_f32 v87, v92, v93
	global_store_dwordx4 v[104:105], v[84:87], off offset:256
	s_cbranch_vccnz .LBB0_980
	v_mov_b32_e32 v100, v237
.LBB0_980:
	s_nop 0
	v_lshlrev_b64 v[84:85], 11, v[172:173]
	v_pk_mul_f32 v[82:83], v[82:83], v[146:147]
	v_pk_mul_f32 v[80:81], v[80:81], v[144:145]
	v_pk_mul_f32 v[78:79], v[78:79], v[142:143]
	v_pk_mul_f32 v[76:77], v[76:77], v[140:141]
	v_lshl_add_u64 v[84:85], v[2:3], 0, v[84:85]
	v_pk_mul_f32 v[82:83], v[82:83], v[100:101] op_sel_hi:[1,0]
	v_pk_mul_f32 v[80:81], v[80:81], v[100:101] op_sel_hi:[1,0]
	v_pk_mul_f32 v[86:87], v[78:79], v[100:101] op_sel_hi:[1,0]
	v_pk_mul_f32 v[78:79], v[76:77], v[100:101] op_sel_hi:[1,0]
	v_cvt_pk_bf16_f32 v76, v80, v81
	v_cvt_pk_bf16_f32 v77, v82, v83
	v_pk_mul_f32 v[70:71], v[70:71], v[134:135]
	v_pk_mul_f32 v[68:69], v[68:69], v[132:133]
	v_cvt_pk_bf16_f32 v78, v78, v79
	v_cvt_pk_bf16_f32 v79, v86, v87
	global_store_dwordx4 v[84:85], v[76:79], off
	v_pk_mul_f32 v[74:75], v[74:75], v[138:139]
	v_pk_mul_f32 v[72:73], v[72:73], v[136:137]
	v_pk_mul_f32 v[76:77], v[70:71], v[100:101] op_sel_hi:[1,0]
	v_pk_mul_f32 v[70:71], v[68:69], v[100:101] op_sel_hi:[1,0]
	v_pk_mul_f32 v[74:75], v[74:75], v[100:101] op_sel_hi:[1,0]
	v_pk_mul_f32 v[72:73], v[72:73], v[100:101] op_sel_hi:[1,0]
	s_and_b64 vcc, exec, s[0:1]
	v_cvt_pk_bf16_f32 v68, v72, v73
	v_cvt_pk_bf16_f32 v69, v74, v75
	v_cvt_pk_bf16_f32 v70, v70, v71
	v_cvt_pk_bf16_f32 v71, v76, v77
	global_store_dwordx4 v[84:85], v[68:71], off offset:256
	s_nop 1
	v_mov_b32_e32 v68, 1.0
	v_mov_b32_e32 v70, 1.0
	s_cbranch_vccnz .LBB0_982
	v_mov_b32_e32 v70, v238
.LBB0_982:
	v_lshlrev_b64 v[72:73], 11, v[168:169]
	v_pk_mul_f32 v[66:67], v[66:67], v[146:147]
	v_pk_mul_f32 v[64:65], v[64:65], v[144:145]
	v_pk_mul_f32 v[62:63], v[62:63], v[142:143]
	v_pk_mul_f32 v[60:61], v[60:61], v[140:141]
	v_lshl_add_u64 v[72:73], v[2:3], 0, v[72:73]
	v_pk_mul_f32 v[66:67], v[66:67], v[70:71] op_sel_hi:[1,0]
	v_pk_mul_f32 v[64:65], v[64:65], v[70:71] op_sel_hi:[1,0]
	v_pk_mul_f32 v[74:75], v[62:63], v[70:71] op_sel_hi:[1,0]
	v_pk_mul_f32 v[62:63], v[60:61], v[70:71] op_sel_hi:[1,0]
	v_cvt_pk_bf16_f32 v60, v64, v65
	v_cvt_pk_bf16_f32 v61, v66, v67
	v_pk_mul_f32 v[54:55], v[54:55], v[134:135]
	v_pk_mul_f32 v[52:53], v[52:53], v[132:133]
	v_cvt_pk_bf16_f32 v62, v62, v63
	v_cvt_pk_bf16_f32 v63, v74, v75
	global_store_dwordx4 v[72:73], v[60:63], off
	v_pk_mul_f32 v[58:59], v[58:59], v[138:139]
	v_pk_mul_f32 v[56:57], v[56:57], v[136:137]
	v_pk_mul_f32 v[60:61], v[54:55], v[70:71] op_sel_hi:[1,0]
	v_pk_mul_f32 v[54:55], v[52:53], v[70:71] op_sel_hi:[1,0]
	s_and_b64 vcc, exec, s[0:1]
	v_pk_mul_f32 v[58:59], v[58:59], v[70:71] op_sel_hi:[1,0]
	v_pk_mul_f32 v[56:57], v[56:57], v[70:71] op_sel_hi:[1,0]
	s_nop 0
	v_cvt_pk_bf16_f32 v52, v56, v57
	v_cvt_pk_bf16_f32 v53, v58, v59
	v_cvt_pk_bf16_f32 v54, v54, v55
	v_cvt_pk_bf16_f32 v55, v60, v61
	global_store_dwordx4 v[72:73], v[52:55], off offset:256
	s_cbranch_vccnz .LBB0_984
	v_mov_b32_e32 v68, v239
.LBB0_984:
	s_nop 0
	v_lshlrev_b64 v[52:53], 11, v[164:165]
	v_pk_mul_f32 v[50:51], v[50:51], v[146:147]
	v_pk_mul_f32 v[48:49], v[48:49], v[144:145]
	v_pk_mul_f32 v[46:47], v[46:47], v[142:143]
	v_pk_mul_f32 v[44:45], v[44:45], v[140:141]
	v_lshl_add_u64 v[52:53], v[2:3], 0, v[52:53]
	v_pk_mul_f32 v[50:51], v[50:51], v[68:69] op_sel_hi:[1,0]
	v_pk_mul_f32 v[48:49], v[48:49], v[68:69] op_sel_hi:[1,0]
	v_pk_mul_f32 v[54:55], v[46:47], v[68:69] op_sel_hi:[1,0]
	v_pk_mul_f32 v[46:47], v[44:45], v[68:69] op_sel_hi:[1,0]
	v_cvt_pk_bf16_f32 v44, v48, v49
	v_cvt_pk_bf16_f32 v45, v50, v51
	v_pk_mul_f32 v[38:39], v[38:39], v[134:135]
	v_pk_mul_f32 v[36:37], v[36:37], v[132:133]
	v_cvt_pk_bf16_f32 v46, v46, v47
	v_cvt_pk_bf16_f32 v47, v54, v55
	global_store_dwordx4 v[52:53], v[44:47], off
	v_pk_mul_f32 v[42:43], v[42:43], v[138:139]
	v_pk_mul_f32 v[40:41], v[40:41], v[136:137]
	v_pk_mul_f32 v[44:45], v[38:39], v[68:69] op_sel_hi:[1,0]
	v_pk_mul_f32 v[38:39], v[36:37], v[68:69] op_sel_hi:[1,0]
	v_pk_mul_f32 v[42:43], v[42:43], v[68:69] op_sel_hi:[1,0]
	v_pk_mul_f32 v[40:41], v[40:41], v[68:69] op_sel_hi:[1,0]
	s_and_b64 vcc, exec, s[0:1]
	v_cvt_pk_bf16_f32 v36, v40, v41
	v_cvt_pk_bf16_f32 v37, v42, v43
	v_cvt_pk_bf16_f32 v38, v38, v39
	v_cvt_pk_bf16_f32 v39, v44, v45
	global_store_dwordx4 v[52:53], v[36:39], off offset:256
	s_nop 1
	v_mov_b32_e32 v36, 1.0
	v_mov_b32_e32 v38, 1.0
	s_cbranch_vccnz .LBB0_986
	v_mov_b32_e32 v38, v240
.LBB0_986:
	v_lshlrev_b64 v[40:41], 11, v[160:161]
	v_pk_mul_f32 v[34:35], v[34:35], v[146:147]
	v_pk_mul_f32 v[32:33], v[32:33], v[144:145]
	v_pk_mul_f32 v[30:31], v[30:31], v[142:143]
	v_pk_mul_f32 v[28:29], v[28:29], v[140:141]
	v_lshl_add_u64 v[40:41], v[2:3], 0, v[40:41]
	v_pk_mul_f32 v[34:35], v[34:35], v[38:39] op_sel_hi:[1,0]
	v_pk_mul_f32 v[32:33], v[32:33], v[38:39] op_sel_hi:[1,0]
	v_pk_mul_f32 v[42:43], v[30:31], v[38:39] op_sel_hi:[1,0]
	v_pk_mul_f32 v[30:31], v[28:29], v[38:39] op_sel_hi:[1,0]
	v_cvt_pk_bf16_f32 v28, v32, v33
	v_cvt_pk_bf16_f32 v29, v34, v35
	v_pk_mul_f32 v[22:23], v[22:23], v[134:135]
	v_pk_mul_f32 v[20:21], v[20:21], v[132:133]
	v_cvt_pk_bf16_f32 v30, v30, v31
	v_cvt_pk_bf16_f32 v31, v42, v43
	global_store_dwordx4 v[40:41], v[28:31], off
	v_pk_mul_f32 v[26:27], v[26:27], v[138:139]
	v_pk_mul_f32 v[24:25], v[24:25], v[136:137]
	v_pk_mul_f32 v[28:29], v[22:23], v[38:39] op_sel_hi:[1,0]
	v_pk_mul_f32 v[22:23], v[20:21], v[38:39] op_sel_hi:[1,0]
	s_and_b64 vcc, exec, s[0:1]
	v_pk_mul_f32 v[26:27], v[26:27], v[38:39] op_sel_hi:[1,0]
	v_pk_mul_f32 v[24:25], v[24:25], v[38:39] op_sel_hi:[1,0]
	s_nop 0
	v_cvt_pk_bf16_f32 v20, v24, v25
	v_cvt_pk_bf16_f32 v21, v26, v27
	v_cvt_pk_bf16_f32 v22, v22, v23
	v_cvt_pk_bf16_f32 v23, v28, v29
	global_store_dwordx4 v[40:41], v[20:23], off offset:256
	s_cbranch_vccnz .LBB0_957
	v_mov_b32_e32 v36, v241
	s_branch .LBB0_957

.LBB0_991:
	s_getreg_b32 s3, hwreg(HW_REG_XCC_ID, 0, 4)
	s_waitcnt vmcnt(0)
	s_waitcnt lgkmcnt(0)
	s_barrier
	s_mov_b64 s[0:1], exec
	v_readlane_b32 s4, v254, 1
	v_readlane_b32 s5, v254, 2
	s_and_b64 s[4:5], s[0:1], s[4:5]
	s_mov_b64 exec, s[4:5]
	s_cbranch_execz .LBB0_1043
	s_and_b32 s18, s3, 15
	s_lshl_b32 s18, s18, 8
	s_add_u32 s12, s30, 0x8d1400
	s_addc_u32 s13, s31, 0
	s_add_u32 s10, s30, 0x8cf400
	s_addc_u32 s11, s31, 0
	s_add_u32 s10, s10, s18
	s_addc_u32 s11, s11, 0
	v_mov_b32_e32 v0, 0x25000
	ds_read_b32 v2, v0
	ds_read_b32 v3, v0 offset:4
	ds_read_b32 v4, v0 offset:8
	v_mov_b32_e32 v1, 1
	v_mov_b32_e32 v5, 0
	global_atomic_add v5, v1, s[10:11]
	s_waitcnt lgkmcnt(0)
	v_readfirstlane_b32 s14, v2
	v_readfirstlane_b32 s15, v3
	v_readfirstlane_b32 s16, v4
	s_nop 3
	s_mul_i32 s14, s14, 7
	s_mul_i32 s15, s15, 7
	s_mov_b32 s17, 0
	s_cmp_eq_u32 s16, 0
	s_cbranch_scc1 .Lxb7_w

.Lnm6b_exit:
.LBB0_1121:
	s_or_b64 exec, exec, s[4:5]
	s_getreg_b32 s3, hwreg(HW_REG_XCC_ID, 0, 4)
	s_waitcnt vmcnt(0)
	s_barrier
	s_mov_b64 s[0:1], exec
	v_readlane_b32 s4, v254, 1
	v_readlane_b32 s5, v254, 2
	s_and_b64 s[4:5], s[0:1], s[4:5]
	s_mov_b64 exec, s[4:5]
	s_cbranch_execz .LBB0_1173
	s_and_b32 s18, s3, 15
	s_lshl_b32 s18, s18, 8
	s_add_u32 s12, s30, 0x8d1400
	s_addc_u32 s13, s31, 0
	s_add_u32 s10, s30, 0x8cf400
	s_addc_u32 s11, s31, 0
	s_add_u32 s10, s10, s18
	s_addc_u32 s11, s11, 0
	v_mov_b32_e32 v0, 0x25000
	ds_read_b32 v2, v0
	ds_read_b32 v3, v0 offset:4
	ds_read_b32 v4, v0 offset:8
	v_mov_b32_e32 v1, 1
	v_mov_b32_e32 v5, 0
	global_atomic_add v5, v1, s[10:11]
	s_waitcnt lgkmcnt(0)
	v_readfirstlane_b32 s14, v2
	v_readfirstlane_b32 s15, v3
	v_readfirstlane_b32 s16, v4
	s_nop 3
	s_mul_i32 s14, s14, 8
	s_mul_i32 s15, s15, 8
	s_mov_b32 s17, 0
	s_cmp_eq_u32 s16, 0
	s_cbranch_scc1 .Lxb8_w

.LBB0_1193:
	s_getreg_b32 s3, hwreg(HW_REG_XCC_ID, 0, 4)
	s_waitcnt vmcnt(0)
	s_waitcnt vmcnt(0) lgkmcnt(0)
	s_barrier
	s_mov_b64 s[0:1], exec
	v_readlane_b32 s4, v254, 1
	v_readlane_b32 s5, v254, 2
	s_and_b64 s[4:5], s[0:1], s[4:5]
	s_mov_b64 exec, s[4:5]
	s_cbranch_execz .LBB0_1245
	s_and_b32 s18, s3, 15
	s_lshl_b32 s18, s18, 8
	s_add_u32 s12, s30, 0x8d1400
	s_addc_u32 s13, s31, 0
	s_add_u32 s10, s30, 0x8cf400
	s_addc_u32 s11, s31, 0
	s_add_u32 s10, s10, s18
	s_addc_u32 s11, s11, 0
	v_mov_b32_e32 v0, 0x25000
	ds_read_b32 v2, v0
	ds_read_b32 v3, v0 offset:4
	ds_read_b32 v4, v0 offset:8
	v_mov_b32_e32 v1, 1
	v_mov_b32_e32 v5, 0
	global_atomic_add v5, v1, s[10:11]
	s_waitcnt lgkmcnt(0)
	v_readfirstlane_b32 s14, v2
	v_readfirstlane_b32 s15, v3
	v_readfirstlane_b32 s16, v4
	s_nop 3
	s_mul_i32 s14, s14, 9
	s_mul_i32 s15, s15, 9
	s_mov_b32 s17, 0
	s_cmp_eq_u32 s16, 0
	s_cbranch_scc1 .Lxb9_w

.LBB0_1269:
	s_getreg_b32 s2, hwreg(HW_REG_XCC_ID, 0, 4)
	s_waitcnt vmcnt(0)
	s_waitcnt lgkmcnt(0)
	s_barrier
	s_mov_b64 s[0:1], exec
	v_readlane_b32 s4, v254, 1
	v_readlane_b32 s5, v254, 2
	s_and_b64 s[4:5], s[0:1], s[4:5]
	s_mov_b64 exec, s[4:5]
	s_cbranch_execz .LBB0_1321
	s_and_b32 s18, s2, 15
	s_lshl_b32 s18, s18, 8
	s_add_u32 s12, s30, 0x8d1400
	s_addc_u32 s13, s31, 0
	s_add_u32 s10, s30, 0x8cf400
	s_addc_u32 s11, s31, 0
	s_add_u32 s10, s10, s18
	s_addc_u32 s11, s11, 0
	v_mov_b32_e32 v0, 0x25000
	ds_read_b32 v2, v0
	ds_read_b32 v3, v0 offset:4
	ds_read_b32 v4, v0 offset:8
	v_mov_b32_e32 v1, 1
	v_mov_b32_e32 v5, 0
	global_atomic_add v5, v1, s[10:11]
	s_waitcnt lgkmcnt(0)
	v_readfirstlane_b32 s14, v2
	v_readfirstlane_b32 s15, v3
	v_readfirstlane_b32 s16, v4
	s_nop 3
	s_mul_i32 s14, s14, 10
	s_mul_i32 s15, s15, 10
	s_mov_b32 s17, 0
	s_cmp_eq_u32 s16, 0
	s_cbranch_scc1 .Lxb10_w
